# cumulative stack on the best kernel: C2 gather de-serialised, 16 tiny exec-skip branches removed, K reads hoisted past the attention barrier, DPP/permlane row reductions in 4 norm phases, DeltaNet sto
# speedup vs baseline: 1.0026x; 1.0026x over previous
.LBB0_705:
	v_mov_b32_e32 v0, s60
	v_cndmask_b32_e64 v155, v111, v0, s[6:7]
	s_add_i32 s18, 16, 0x21000
	s_add_i32 s19, 16, 0x8800
	v_mov_b32_e32 v3, v120
	v_mov_b32_e32 v0, v107
	v_mov_b32_e32 v74, v121
	s_and_b64 s[0:1], s[14:15], exec
	s_waitcnt lgkmcnt(0)
	s_barrier
	s_cselect_b32 s0, s19, s18
	v_mul_lo_u32 v0, v3, s24
	s_add_i32 s1, 16, 0x16400
	v_lshlrev_b32_e32 v68, 3, v74
	v_add3_u32 v0, s1, v0, v68
	v_add_u32_e32 v1, 0x1000, v0
	v_mul_lo_u32 v69, v3, 40
	v_lshl_add_u32 v3, v3, 1, s43
	v_mul_lo_u32 v74, v74, s25
	ds_read_b64 v[64:65], v1 offset:512
	ds_read_b64 v[66:67], v1 offset:544
	v_add_u32_e32 v1, 0x1800, v0
	v_add3_u32 v68, s40, v68, v69
	v_add_u32_e32 v156, v3, v74
	ds_read_b64 v[72:73], v0 offset:2304
	ds_read_b64 v[60:61], v1 offset:768
	ds_read_b64 v[62:63], v1 offset:800
	ds_read_b64 v[0:1], v0 offset:6976
	ds_read_b64 v[84:85], v68
	ds_read_b64 v[86:87], v68 offset:640
	ds_read_b64 v[70:71], v68 offset:1920
	ds_read_b64 v[68:69], v68 offset:1280
	ds_read_u16 v188, v156 offset:61696
	v_add_u32_e32 v75, 0xd000, v3
	v_add_u32_e32 v101, 0x6510, v74
	v_add_u32_e32 v162, v75, v101
	ds_read_u16 v77, v162
	ds_read_u16 v189, v156 offset:62224
	v_add_u32_e32 v102, 0x6720, v74
	v_add_u32_e32 v163, v75, v102
	ds_read_u16 v78, v163
	v_add_u32_e32 v100, 0x6300, v74
	ds_read_u16 v190, v156 offset:62752
	v_add_u32_e32 v96, 0x4200, v74
	v_add_u32_e32 v97, 0x4410, v74
	v_add_u32_e32 v98, 0x4620, v74
	v_add_u32_e32 v99, 0x4830, v74
	v_add_u32_e32 v74, 0x6930, v74
	v_add_u32_e32 v164, v75, v74
	v_add_u32_e32 v157, v75, v96
	v_add_u32_e32 v158, v75, v97
	v_add_u32_e32 v159, v75, v98
	v_add_u32_e32 v160, v75, v99
	v_add_u32_e32 v161, v75, v100
	ds_read_u16 v192, v164
	ds_read_u16 v191, v156 offset:63280
	v_add_u32_e32 v75, 0xd020, v3
	ds_read_u16 v193, v157
	v_add_u32_e32 v181, v75, v97
	v_add_u32_e32 v185, v75, v101
	v_add_u32_e32 v182, v75, v98
	v_add_u32_e32 v186, v75, v102
	ds_read_u16 v194, v158
	v_add_u32_e32 v180, v75, v96
	v_add_u32_e32 v183, v75, v99
	v_add_u32_e32 v184, v75, v100
	v_add_u32_e32 v187, v75, v74
	ds_read_u16 v195, v159
	ds_read_u16 v196, v160
	ds_read_u16 v76, v161
	s_waitcnt lgkmcnt(1)
	v_lshlrev_b32_e32 v88, 16, v188
	v_lshlrev_b32_e32 v89, 16, v189
	v_lshlrev_b32_e32 v90, 16, v190
	v_lshlrev_b32_e32 v77, 16, v77
	v_lshlrev_b32_e32 v78, 16, v78
	v_lshlrev_b32_e32 v79, 16, v192
	v_lshlrev_b32_e32 v91, 16, v191
	v_lshlrev_b32_e32 v80, 16, v193
	v_lshlrev_b32_e32 v81, 16, v194
	v_lshlrev_b32_e32 v82, 16, v195
	v_lshlrev_b32_e32 v83, 16, v196
	ds_read_u16 v168, v156 offset:53248
	ds_read_u16 v3, v156 offset:53280
	ds_read_u16 v197, v156 offset:53808
	ds_read_u16 v93, v156 offset:62256
	ds_read_u16 v97, v181
	ds_read_u16 v101, v185
	ds_read_u16 v94, v156 offset:62784
	ds_read_u16 v98, v182
	ds_read_u16 v102, v186
	ds_read_u16 v198, v156 offset:54336
	ds_read_u16 v95, v156 offset:63312
	ds_read_u16 v99, v183
	ds_read_u16 v74, v187
	ds_read_u16 v96, v180
	ds_read_u16 v100, v184
	ds_read_u16 v199, v156 offset:54864
	ds_read_u16 v92, v156 offset:61728
	ds_read_u16 v169, v156 offset:54832
	ds_read_u16 v170, v156 offset:53776
	ds_read_u16 v171, v156 offset:54304
	s_waitcnt lgkmcnt(13)
	v_lshlrev_b32_e32 v3, 16, v3
	v_lshlrev_b32_e32 v76, 16, v76
	v_lshlrev_b32_e32 v93, 16, v93
	v_lshlrev_b32_e32 v94, 16, v94
	s_waitcnt lgkmcnt(6)
	v_lshlrev_b32_e32 v95, 16, v95
	v_lshlrev_b32_e32 v96, 16, v96
	v_lshlrev_b32_e32 v97, 16, v97
	s_waitcnt lgkmcnt(3)
	v_lshlrev_b32_e32 v92, 16, v92
	v_lshlrev_b32_e32 v98, 16, v98
	v_lshlrev_b32_e32 v99, 16, v99
	v_lshlrev_b32_e32 v100, 16, v100
	v_lshlrev_b32_e32 v101, 16, v101
	v_lshlrev_b32_e32 v102, 16, v102
	v_lshlrev_b32_e32 v103, 16, v74
	v_lshlrev_b32_e32 v165, 16, v197
	v_lshlrev_b32_e32 v166, 16, v198
	v_lshlrev_b32_e32 v167, 16, v199
	v_mov_b32_e32 v140, v84
	v_mov_b32_e32 v141, v85
	v_mov_b32_e32 v142, v2
	v_mov_b32_e32 v143, v2
	s_waitcnt lgkmcnt(2)
	v_lshlrev_b32_e32 v84, 16, v169
	v_lshlrev_b32_e32 v85, 16, v168
	s_waitcnt lgkmcnt(1)
	v_lshlrev_b32_e32 v168, 16, v170
	s_waitcnt lgkmcnt(0)
	v_lshlrev_b32_e32 v169, 16, v171
	v_cvt_pk_bf16_f32 v169, v169, v84
	v_cvt_pk_bf16_f32 v168, v85, v168
	v_mov_b32_e32 v170, v2
	v_mov_b32_e32 v171, v2
	v_mov_b32_e32 v74, v2
	v_mov_b32_e32 v75, v2
	v_mfma_f32_16x16x32_bf16 v[168:171], v[140:143], v[168:171], 0
	v_cvt_pk_bf16_f32 v173, v166, v167
	v_cvt_pk_bf16_f32 v172, v3, v165
	v_mov_b32_e32 v174, v2
	v_mov_b32_e32 v175, v2
	v_mov_b32_e32 v84, v86
	v_mov_b32_e32 v85, v87
	v_mfma_f32_16x16x32_bf16 v[140:143], v[140:143], v[172:175], 0
	s_nop 0
	v_cvt_pk_bf16_f32 v173, v170, v171
	v_cvt_pk_bf16_f32 v172, v168, v169
	v_mov_b32_e32 v86, v2
	v_mov_b32_e32 v87, v2
	v_mfma_f32_16x16x32_bf16 v[88:91], v[72:75], v[172:175], v[88:91]
	v_mov_b32_e32 v176, v2
	v_mov_b32_e32 v177, v2
	v_mov_b32_e32 v178, v2
	v_mov_b32_e32 v179, v2
	v_mov_b32_e32 v3, v2
	s_nop 2
	v_cvt_pk_bf16_f32 v175, v90, v91
	v_cvt_pk_bf16_f32 v174, v88, v89
	s_cmp_lg_u32 16, -1
	s_cselect_b32 s1, s41, 0
	v_mfma_f32_16x16x32_bf16 v[88:91], v[84:87], v[174:177], 0
	v_cvt_pk_bf16_f32 v177, v142, v143
	v_cvt_pk_bf16_f32 v176, v140, v141
	s_nop 1
	v_mfma_f32_16x16x32_bf16 v[72:75], v[72:75], v[176:179], v[92:95]
	s_nop 2
	v_cvt_pk_bf16_f32 v175, v90, v91
	v_cvt_pk_bf16_f32 v174, v88, v89
	v_mov_b32_e32 v94, v2
	v_mov_b32_e32 v95, v2
	s_nop 0
	v_cvt_pk_bf16_f32 v93, v74, v75
	v_cvt_pk_bf16_f32 v92, v72, v73
	v_mfma_f32_16x16x32_bf16 v[80:83], v[64:67], v[172:175], v[80:83]
	s_nop 0
	v_mfma_f32_16x16x32_bf16 v[72:75], v[84:87], v[92:95], 0
	v_mov_b32_e32 v84, v68
	v_mov_b32_e32 v85, v69
	s_nop 3
	v_cvt_pk_bf16_f32 v93, v82, v83
	v_cvt_pk_bf16_f32 v92, v80, v81
	v_mfma_f32_16x16x32_bf16 v[76:79], v[60:63], v[172:175], v[76:79]
	v_cvt_pk_bf16_f32 v179, v74, v75
	v_cvt_pk_bf16_f32 v178, v72, v73
	v_mov_b32_e32 v68, v2
	v_mfma_f32_16x16x32_bf16 v[80:83], v[84:87], v[92:95], 0
	v_mov_b32_e32 v69, v2
	v_mfma_f32_16x16x32_bf16 v[64:67], v[64:67], v[176:179], v[96:99]
	v_mfma_f32_16x16x32_bf16 v[60:63], v[60:63], v[176:179], v[100:103]
	s_nop 6
	v_cvt_pk_bf16_f32 v67, v66, v67
	v_cvt_pk_bf16_f32 v66, v64, v65
	s_nop 1
	v_mfma_f32_16x16x32_bf16 v[64:67], v[84:87], v[66:69], 0
	v_cvt_pk_bf16_f32 v85, v82, v83
	v_cvt_pk_bf16_f32 v84, v80, v81
	v_mov_b32_e32 v68, v70
	v_mov_b32_e32 v69, v71
	v_mov_b32_e32 v70, v2
	v_mov_b32_e32 v71, v2
	v_mfma_f32_16x16x32_bf16 v[76:79], v[0:3], v[84:87], v[76:79]
	s_nop 7
	v_cvt_pk_bf16_f32 v85, v78, v79
	v_cvt_pk_bf16_f32 v84, v76, v77
	s_nop 1
	v_mfma_f32_16x16x32_bf16 v[76:79], v[68:71], v[84:87], 0
	v_cvt_pk_bf16_f32 v85, v66, v67
	v_cvt_pk_bf16_f32 v84, v64, v65
	s_nop 1
	v_mfma_f32_16x16x32_bf16 v[60:63], v[0:3], v[84:87], v[60:63]
	v_cvt_pk_bf16_f32 v87, v30, v31
	v_cvt_pk_bf16_f32 v86, v28, v29
	v_cvt_pk_bf16_f32 v85, v34, v35
	v_cvt_pk_bf16_f32 v84, v32, v33
	s_nop 3
	v_cvt_pk_bf16_f32 v1, v62, v63
	v_cvt_pk_bf16_f32 v0, v60, v61
	s_nop 1
	v_mfma_f32_16x16x32_bf16 v[60:63], v[68:71], v[0:3], 0
	v_cvt_pk_bf16_f32 v0, v168, s0
	ds_write_b16 v156, v0 offset:53248
	v_cvt_pk_bf16_f32 v0, v169, s0
	ds_write_b16 v156, v0 offset:53776
	v_cvt_pk_bf16_f32 v0, v170, s0
	ds_write_b16 v156, v0 offset:54304
	v_cvt_pk_bf16_f32 v0, v171, s0
	ds_write_b16 v156, v0 offset:54832
	v_cvt_pk_bf16_f32 v0, v88, s0
	ds_write_b16 v156, v0 offset:61696
	v_cvt_pk_bf16_f32 v0, v89, s0
	ds_write_b16 v156, v0 offset:62224
	v_cvt_pk_bf16_f32 v0, v90, s0
	ds_write_b16 v156, v0 offset:62752
	v_cvt_pk_bf16_f32 v0, v91, s0
	ds_write_b16 v156, v0 offset:63280
	v_cvt_pk_bf16_f32 v0, v80, s0
	ds_write_b16 v157, v0
	v_cvt_pk_bf16_f32 v0, v81, s0
	ds_write_b16 v158, v0
	v_cvt_pk_bf16_f32 v0, v82, s0
	ds_write_b16 v159, v0
	v_cvt_pk_bf16_f32 v0, v83, s0
	ds_write_b16 v160, v0
	v_cvt_pk_bf16_f32 v0, v76, s0
	ds_write_b16 v161, v0
	v_cvt_pk_bf16_f32 v0, v77, s0
	ds_write_b16 v162, v0
	v_cvt_pk_bf16_f32 v0, v78, s0
	ds_write_b16 v163, v0
	v_cvt_pk_bf16_f32 v0, v79, s0
	ds_write_b16 v164, v0
	v_cvt_pk_bf16_f32 v0, v140, s0
	ds_write_b16 v156, v0 offset:53280
	v_cvt_pk_bf16_f32 v0, v141, s0
	ds_write_b16 v156, v0 offset:53808
	v_cvt_pk_bf16_f32 v0, v142, s0
	ds_write_b16 v156, v0 offset:54336
	v_cvt_pk_bf16_f32 v0, v143, s0
	ds_write_b16 v156, v0 offset:54864
	v_cvt_pk_bf16_f32 v0, v72, s0
	ds_write_b16 v156, v0 offset:61728
	v_cvt_pk_bf16_f32 v0, v73, s0
	ds_write_b16 v156, v0 offset:62256
	v_cvt_pk_bf16_f32 v0, v74, s0
	ds_write_b16 v156, v0 offset:62784
	v_cvt_pk_bf16_f32 v0, v75, s0
	ds_write_b16 v156, v0 offset:63312
	v_cvt_pk_bf16_f32 v0, v64, s0
	ds_write_b16 v180, v0
	v_cvt_pk_bf16_f32 v0, v65, s0
	ds_write_b16 v181, v0
	v_cvt_pk_bf16_f32 v0, v66, s0
	ds_write_b16 v182, v0
	v_cvt_pk_bf16_f32 v0, v67, s0
	ds_write_b16 v183, v0
	v_cvt_pk_bf16_f32 v0, v60, s0
	ds_write_b16 v184, v0
	v_cvt_pk_bf16_f32 v0, v61, s0
	ds_write_b16 v185, v0
	v_cvt_pk_bf16_f32 v0, v62, s0
	ds_write_b16 v186, v0
	v_cvt_pk_bf16_f32 v0, v63, s0
	v_mov_b32_e32 v3, v107
	v_mov_b32_e32 v88, v120
	v_mov_b32_e32 v89, v121
	ds_write_b16 v187, v0
	s_waitcnt lgkmcnt(0)
	s_barrier
	v_cvt_pk_bf16_f32 v63, v6, v7
	v_mul_lo_u32 v0, v88, s22
	v_lshlrev_b32_e32 v90, 3, v89
	v_add3_u32 v164, 16, v0, v90
	v_add_u32_e32 v0, 0xd000, v164
	ds_read_b64 v[72:73], v0 offset:256
	ds_read_b64 v[74:75], v0 offset:288
	ds_read_b64 v[76:77], v0 offset:320
	ds_read_b64 v[78:79], v0 offset:352
	v_cvt_pk_bf16_f32 v62, v4, v5
	v_cvt_pk_bf16_f32 v61, v10, v11
	v_cvt_pk_bf16_f32 v60, v8, v9
	ds_read_b64 v[80:81], v0 offset:384
	ds_read_b64 v[82:83], v0 offset:416
	v_cvt_pk_bf16_f32 v67, v14, v15
	s_waitcnt lgkmcnt(4)
	v_mfma_f32_16x16x32_bf16 v[72:75], v[72:75], v[60:63], 0
	v_cvt_pk_bf16_f32 v66, v12, v13
	v_cvt_pk_bf16_f32 v65, v18, v19
	v_cvt_pk_bf16_f32 v64, v16, v17
	ds_read_b64 v[92:93], v0 offset:448
	ds_read_b64 v[94:95], v0 offset:480
	v_mul_lo_u32 v0, v88, s21
	s_waitcnt lgkmcnt(4)
	v_mfma_f32_16x16x32_bf16 v[72:75], v[76:79], v[64:67], v[72:75]
	v_cvt_pk_bf16_f32 v71, v22, v23
	v_cvt_pk_bf16_f32 v70, v20, v21
	v_cvt_pk_bf16_f32 v69, v26, v27
	v_cvt_pk_bf16_f32 v68, v24, v25
	v_add3_u32 v165, s66, v90, v0
	ds_read_b64 v[76:77], v165
	ds_read_b64 v[78:79], v165 offset:32
	s_waitcnt lgkmcnt(4)
	v_mfma_f32_16x16x32_bf16 v[72:75], v[80:83], v[68:71], v[72:75]
	v_add_u32_e32 v1, 0xf000, v164
	ds_read_b64 v[98:99], v1 offset:640
	ds_read_b64 v[100:101], v1 offset:672
	v_add_u32_e32 v91, 0x1000, v165
	s_waitcnt lgkmcnt(4)
	v_mfma_f32_16x16x32_bf16 v[80:83], v[92:95], v[84:87], v[72:75]
	ds_read_b64 v[92:93], v165 offset:128
	ds_read_b64 v[94:95], v165 offset:160
	v_lshl_add_u32 v0, v88, 1, s61
	v_mad_u64_u32 v[102:103], s[12:13], v89, s25, v[0:1]
	ds_read_b64 v[72:73], v165 offset:64
	ds_read_b64 v[74:75], v165 offset:96
	s_waitcnt lgkmcnt(6)
	v_mfma_f32_16x16x32_bf16 v[76:79], v[76:79], v[60:63], 0
	s_waitcnt lgkmcnt(0)
	v_mfma_f32_16x16x32_bf16 v[72:75], v[72:75], v[64:67], v[76:79]
	s_nop 5
	ds_read_b64 v[76:77], v165 offset:192
	ds_read_b64 v[78:79], v165 offset:224
	v_mfma_f32_16x16x32_bf16 v[72:75], v[92:95], v[68:71], v[72:75]
	ds_read_b64 v[94:95], v1 offset:512
	ds_read_b64 v[96:97], v1 offset:544
	v_lshlrev_b32_e32 v92, 2, v89
	v_or_b32_e32 v176, 1, v92
	s_waitcnt lgkmcnt(2)
	v_mfma_f32_16x16x32_bf16 v[72:75], v[76:79], v[84:87], v[72:75]
	ds_read_b64 v[76:77], v1 offset:576
	ds_read_b64 v[78:79], v1 offset:608
	v_mad_u64_u32 v[160:161], s[12:13], v176, s22, v[0:1]
	s_waitcnt lgkmcnt(2)
	v_mfma_f32_16x16x32_bf16 v[94:97], v[94:97], v[60:63], 0
	v_add_u32_e32 v172, 0x1ef0, v160
	s_cselect_b32 s12, 16, 0
	s_add_u32 s12, s12, 0x1c8fc
	s_waitcnt lgkmcnt(0)
	v_mfma_f32_16x16x32_bf16 v[76:79], v[76:79], v[64:67], v[94:97]
	s_addc_u32 s13, s1, 0
	s_nop 1
	ds_read_b64 v[94:95], v91 offset:256
	ds_read_b64 v[96:97], v91 offset:288
	s_cmp_lg_u64 s[6:7], 0
	s_cselect_b32 s99, 0, -1
	s_cselect_b32 s101, 0, -1
	s_cselect_b32 s98, 1, -1
	s_lshl_b32 s98, s98, 12
	s_lshl_b32 s100, s98, 4
	s_cmp_lg_u64 s[12:13], 0
	v_mfma_f32_16x16x32_bf16 v[76:79], v[98:101], v[68:71], v[76:79]
	ds_read_b64 v[98:99], v1 offset:704
	ds_read_b64 v[100:101], v1 offset:736
	ds_read_u16 v0, v102 offset:53248
	ds_read_u16 v1, v160 offset:53248
	ds_read_u16 v93, v160 offset:53776
	ds_read_u16 v102, v160 offset:54304
	ds_read_u16 v161, v160 offset:61168
	ds_read_u16 v162, v160 offset:61696
	ds_read_u16 v166, v160 offset:62224
	ds_read_u16 v167, v160 offset:62752
	ds_read_b64 v[140:141], v91 offset:320
	ds_read_b64 v[142:143], v91 offset:352
	s_waitcnt lgkmcnt(8)
	v_lshlrev_b32_e32 v1, 16, v1
	v_mfma_f32_16x16x32_bf16 v[94:97], v[94:97], v[60:63], 0
	v_lshlrev_b32_e32 v0, 16, v0
	v_pk_add_f32 v[0:1], v[0:1], v[80:81] neg_lo:[0,1] neg_hi:[0,1]
	v_add_u32_e32 v80, 0x4200, v164
	v_mfma_f32_16x16x32_bf16 v[98:101], v[98:101], v[84:87], v[76:79]
	v_add_u32_e32 v168, 0xd000, v80
	s_waitcnt lgkmcnt(6)
	v_lshlrev_b32_e32 v81, 16, v102
	ds_read_b64 v[156:157], v91 offset:448
	ds_read_b64 v[158:159], v91 offset:480
	ds_read_b64 v[76:77], v91 offset:384
	ds_read_b64 v[78:79], v91 offset:416
	s_waitcnt lgkmcnt(4)
	v_mfma_f32_16x16x32_bf16 v[94:97], v[140:143], v[64:67], v[94:97]
	ds_read_b64 v[140:141], v168 offset:256
	ds_read_b64 v[142:143], v168 offset:288
	v_lshlrev_b32_e32 v80, 16, v93
	v_pk_add_f32 v[102:103], v[80:81], v[82:83] neg_lo:[0,1] neg_hi:[0,1]
	ds_read_b64 v[80:81], v168 offset:320
	ds_read_b64 v[82:83], v168 offset:352
	s_waitcnt lgkmcnt(4)
	v_mfma_f32_16x16x32_bf16 v[76:79], v[76:79], v[68:71], v[94:97]
	s_nop 2
	ds_read_b64 v[94:95], v168 offset:384
	ds_read_b64 v[96:97], v168 offset:416
	v_add_u32_e32 v93, 0x2000, v165
	v_lshlrev_b32_e32 v163, 16, v162
	s_waitcnt lgkmcnt(4)
	v_mfma_f32_16x16x32_bf16 v[140:143], v[140:143], v[60:63], 0
	v_lshlrev_b32_e32 v162, 16, v161
	v_add_u32_e32 v165, 0x3000, v165
	s_cselect_b32 s1, s12, -1
	v_mfma_f32_16x16x32_bf16 v[76:79], v[156:159], v[84:87], v[76:79]
	ds_read_b64 v[156:157], v168 offset:448
	ds_read_b64 v[158:159], v168 offset:480
	v_pk_add_f32 v[168:169], v[162:163], v[98:99] neg_lo:[0,1] neg_hi:[0,1]
	v_lshlrev_b32_e32 v99, 16, v167
	s_waitcnt lgkmcnt(4)
	v_mfma_f32_16x16x32_bf16 v[80:83], v[80:83], v[64:67], v[140:143]
	v_lshlrev_b32_e32 v98, 16, v166
	v_pk_add_f32 v[170:171], v[98:99], v[100:101] neg_lo:[0,1] neg_hi:[0,1]
	ds_read_b64 v[98:99], v93 offset:704
	ds_read_b64 v[100:101], v93 offset:736
	ds_read_b64 v[140:141], v93 offset:512
	ds_read_b64 v[142:143], v93 offset:544
	s_waitcnt lgkmcnt(6)
	v_mfma_f32_16x16x32_bf16 v[80:83], v[94:97], v[68:71], v[80:83]
	ds_read_b64 v[94:95], v93 offset:576
	ds_read_b64 v[96:97], v93 offset:608
	s_add_i32 s66, 16, 0x258fc
	s_and_b64 s[12:13], s[14:15], exec
	s_waitcnt lgkmcnt(6)
	v_mfma_f32_16x16x32_bf16 v[156:159], v[156:159], v[84:87], v[80:83]
	s_cselect_b32 s1, s1, s66
	s_nop 0
	ds_read_b64 v[80:81], v93 offset:640
	ds_read_b64 v[82:83], v93 offset:672
	s_waitcnt lgkmcnt(4)
	v_mfma_f32_16x16x32_bf16 v[140:143], v[140:143], v[60:63], 0
	v_add_u32_e32 v91, 16, v92
	s_waitcnt lgkmcnt(2)
	v_mfma_f32_16x16x32_bf16 v[94:97], v[94:97], v[64:67], v[140:143]
	v_add_u32_e32 v93, 32, v92
	s_waitcnt lgkmcnt(0)
	v_mfma_f32_16x16x32_bf16 v[80:83], v[80:83], v[68:71], v[94:97]
	s_nop 1
	v_add_u32_e32 v140, 0x3ff0, v160
	s_nop 1
	v_add_u32_e32 v94, 0x6300, v164
	v_add_u32_e32 v162, 0xd000, v94
	ds_read_b64 v[94:95], v162 offset:256
	ds_read_b64 v[96:97], v162 offset:288
	ds_read_u16 v160, v172 offset:61696
	ds_read_u16 v141, v172 offset:62224
	ds_read_u16 v164, v172 offset:62752
	ds_read_u16 v166, v172 offset:63280
	ds_read_u16 v183, v140 offset:61696
	ds_read_u16 v184, v140 offset:62224
	ds_read_u16 v185, v140 offset:62752
	ds_read_u16 v186, v140 offset:63280
	s_waitcnt lgkmcnt(6)
	v_lshlrev_b32_e32 v161, 16, v141
	ds_read_b64 v[140:141], v162 offset:320
	ds_read_b64 v[142:143], v162 offset:352
	v_mfma_f32_16x16x32_bf16 v[80:83], v[98:101], v[84:87], v[80:83]
	ds_read_b64 v[98:99], v162 offset:384
	ds_read_b64 v[100:101], v162 offset:416
	v_lshlrev_b32_e32 v160, 16, v160
	v_pk_add_f32 v[172:173], v[160:161], v[156:157] neg_lo:[0,1] neg_hi:[0,1]
	v_mfma_f32_16x16x32_bf16 v[94:97], v[94:97], v[60:63], 0
	ds_read_b64 v[160:161], v162 offset:448
	ds_read_b64 v[162:163], v162 offset:480
	s_waitcnt lgkmcnt(10)
	v_lshlrev_b32_e32 v157, 16, v166
	v_lshlrev_b32_e32 v156, 16, v164
	s_waitcnt lgkmcnt(4)
	v_mfma_f32_16x16x32_bf16 v[94:97], v[140:143], v[64:67], v[94:97]
	ds_read_b64 v[140:141], v165 offset:768
	ds_read_b64 v[142:143], v165 offset:800
	v_pk_add_f32 v[174:175], v[156:157], v[158:159] neg_lo:[0,1] neg_hi:[0,1]
	s_waitcnt lgkmcnt(4)
	v_mfma_f32_16x16x32_bf16 v[94:97], v[98:101], v[68:71], v[94:97]
	ds_read_b64 v[98:99], v165 offset:832
	ds_read_b64 v[100:101], v165 offset:864
	s_add_i32 s60, s60, 1
	v_cmp_lt_u32_e32 vcc, s60, v109
	s_waitcnt lgkmcnt(2)
	v_mfma_f32_16x16x32_bf16 v[60:63], v[140:143], v[60:63], 0
	v_mfma_f32_16x16x32_bf16 v[156:159], v[160:163], v[84:87], v[94:97]
	ds_read_b64 v[160:161], v165 offset:896
	ds_read_b64 v[162:163], v165 offset:928
	ds_read_b64 v[166:167], v165 offset:992
	ds_read_b64 v[164:165], v165 offset:960
	s_nop 0
	v_lshlrev_b32_e32 v97, 16, v184
	s_waitcnt lgkmcnt(4)
	v_mfma_f32_16x16x32_bf16 v[60:63], v[98:101], v[64:67], v[60:63]
	v_lshlrev_b32_e32 v65, 16, v186
	v_lshlrev_b32_e32 v64, 16, v185
	v_lshlrev_b32_e32 v96, 16, v183
	s_waitcnt lgkmcnt(2)
	v_mfma_f32_16x16x32_bf16 v[60:63], v[160:163], v[68:71], v[60:63]
	v_add_f32_e64 v64, v64, -v158
	v_add_f32_e64 v65, v65, -v159
	v_mul_lo_u32 v159, v88, s24
	v_pk_add_f32 v[96:97], v[96:97], v[156:157] neg_lo:[0,1] neg_hi:[0,1]
	s_waitcnt lgkmcnt(0)
	v_mfma_f32_16x16x32_bf16 v[68:71], v[164:167], v[84:87], v[60:63]
	v_cvt_pk_bf16_f32 v66, v96, v97
	v_cvt_pk_bf16_f32 v67, v64, v65
	v_cvt_pk_bf16_f32 v65, v174, v175
	v_cvt_pk_bf16_f32 v60, v0, v1
	v_mov_b32_e32 v0, s1
	s_add_i32 s1, 16, 0x19200
	v_add_u32_e32 v158, s1, v90
	v_add_u32_e32 v84, v158, v159
	ds_read_b64 v[96:97], v84
	ds_read_b64 v[98:99], v84 offset:32
	ds_read_b32 v0, v0
	v_cvt_pk_bf16_f32 v61, v102, v103
	ds_read_b64 v[100:101], v84 offset:64
	ds_read_b64 v[102:103], v84 offset:96
	v_cvt_pk_bf16_f32 v63, v170, v171
	v_cvt_pk_bf16_f32 v62, v168, v169
	s_waitcnt lgkmcnt(2)
	v_mul_f32_e32 v157, 0x3fb8aa3b, v0
	v_lshlrev_b32_e32 v0, 6, v155
	v_lshl_add_u32 v155, v89, 4, s65
	ds_read_b128 v[140:143], v155
	v_ashrrev_i32_e32 v89, 31, v88
	v_lshl_add_u64 v[84:85], v[88:89], 2, v[116:117]
	v_mfma_f32_16x16x32_bf16 v[86:89], v[96:99], v[60:63], 0
	v_cvt_pk_bf16_f32 v64, v172, v173
	ds_read_b128 v[96:99], v155 offset:64
	s_waitcnt lgkmcnt(1)
	v_mul_f32_e32 v140, 0x3fb8aa3b, v140
	v_exp_f32_e32 v140, v140
	v_mfma_f32_16x16x32_bf16 v[86:89], v[100:103], v[64:67], v[86:89]
	v_sub_u32_e32 v100, 63, v92
	v_ashrrev_i32_e32 v1, 31, v0
	v_cndmask_b32_e64 v100, v100, v92, s[6:7]
	v_lshl_add_u64 v[0:1], v[0:1], 0, v[104:105]
	v_ashrrev_i32_e32 v101, 31, v100
	s_nop 2
	v_fma_f32 v72, v72, v140, v86
	v_lshl_add_u64 v[100:101], v[0:1], 0, v[100:101]
	v_mul_f32_e32 v86, 0x3fb8aa3b, v141
	v_lshlrev_b64 v[100:101], 12, v[100:101]
	v_exp_f32_e32 v86, v86
	v_lshl_add_u64 v[194:195], v[84:85], 0, v[100:101]
	global_store_dword v[194:195], v72, off
	v_fma_f32 v86, v73, v86, v87
	v_lshl_add_u64 v[190:191], v[194:195], 0, s[98:99]
	v_mul_f32_e32 v87, 0x3fb8aa3b, v142
	global_store_dword v[190:191], v86, off
	v_exp_f32_e32 v87, v87
	s_nop 0
	v_fma_f32 v74, v74, v87, v88
	v_lshl_add_u64 v[192:193], v[190:191], 0, s[98:99]
	v_add_u32_e32 v140, 0x900, v159
	global_store_dword v[192:193], v74, off
	v_mul_f32_e32 v72, 0x3fb8aa3b, v143
	v_add_u32_e32 v73, v158, v140
	v_exp_f32_e32 v72, v72
	ds_read_b64 v[100:101], v73
	ds_read_b64 v[102:103], v73 offset:32
	v_fmac_f32_e32 v89, v75, v72
	ds_read_b64 v[74:75], v73 offset:96
	ds_read_b64 v[72:73], v73 offset:64
	s_waitcnt lgkmcnt(2)
	v_mfma_f32_16x16x32_bf16 v[100:103], v[100:103], v[60:63], 0
	v_lshl_add_u64 v[190:191], v[192:193], 0, s[98:99]
	global_store_dword v[190:191], v89, off
	v_mul_f32_e32 v86, 0x3fb8aa3b, v96
	v_exp_f32_e32 v87, v86
	s_waitcnt lgkmcnt(0)
	v_mfma_f32_16x16x32_bf16 v[72:75], v[72:75], v[64:67], v[100:103]
	v_add_u32_e32 v141, 0x1200, v159
	s_nop 0
	ds_read_b128 v[100:103], v155 offset:128
	v_add_u32_e32 v94, 48, v92
	s_nop 2
	s_nop 0
	v_fma_f32 v72, v76, v87, v72
	v_mul_f32_e32 v76, 0x3fb8aa3b, v97
	v_exp_f32_e32 v76, v76
	v_lshl_add_u64 v[194:195], v[194:195], 0, s[100:101]
	global_store_dword v[194:195], v72, off
	v_fma_f32 v76, v77, v76, v73
	v_lshl_add_u64 v[190:191], v[194:195], 0, s[98:99]
	v_mul_f32_e32 v77, 0x3fb8aa3b, v98
	global_store_dword v[190:191], v76, off
	v_exp_f32_e32 v77, v77
	s_nop 0
	v_fma_f32 v74, v78, v77, v74
	v_lshl_add_u64 v[192:193], v[190:191], 0, s[98:99]
	global_store_dword v[192:193], v74, off
	v_add_u32_e32 v74, v158, v141
	v_mul_f32_e32 v73, 0x3fb8aa3b, v99
	ds_read_b64 v[86:87], v74
	ds_read_b64 v[88:89], v74 offset:32
	v_exp_f32_e32 v73, v73
	ds_read_b64 v[96:97], v74 offset:64
	ds_read_b64 v[98:99], v74 offset:96
	v_fmac_f32_e32 v75, v79, v73
	v_lshl_add_u64 v[190:191], v[192:193], 0, s[98:99]
	global_store_dword v[190:191], v75, off
	s_waitcnt lgkmcnt(2)
	v_mfma_f32_16x16x32_bf16 v[72:75], v[86:89], v[60:63], 0
	ds_read_b128 v[76:79], v155 offset:192
	v_mul_f32_e32 v86, 0x3fb8aa3b, v100
	v_exp_f32_e32 v87, v86
	s_waitcnt lgkmcnt(1)
	v_mfma_f32_16x16x32_bf16 v[72:75], v[96:99], v[64:67], v[72:75]
	v_add_u32_e32 v100, 0x1b00, v159
	s_nop 2
	s_nop 1
	s_nop 1
	v_fma_f32 v72, v80, v87, v72
	v_mul_f32_e32 v80, 0x3fb8aa3b, v101
	v_exp_f32_e32 v80, v80
	v_lshl_add_u64 v[194:195], v[194:195], 0, s[100:101]
	global_store_dword v[194:195], v72, off
	v_fma_f32 v80, v81, v80, v73
	v_lshl_add_u64 v[190:191], v[194:195], 0, s[98:99]
	v_mul_f32_e32 v81, 0x3fb8aa3b, v102
	global_store_dword v[190:191], v80, off
	v_exp_f32_e32 v81, v81
	s_nop 0
	v_fma_f32 v74, v82, v81, v74
	v_lshl_add_u64 v[192:193], v[190:191], 0, s[98:99]
	global_store_dword v[192:193], v74, off
	v_mul_f32_e32 v72, 0x3fb8aa3b, v103
	v_add_u32_e32 v74, v158, v100
	v_exp_f32_e32 v73, v72
	ds_read_b64 v[86:87], v74
	ds_read_b64 v[88:89], v74 offset:32
	v_fmac_f32_e32 v75, v83, v73
	ds_read_b64 v[80:81], v74 offset:64
	ds_read_b64 v[82:83], v74 offset:96
	s_waitcnt lgkmcnt(2)
	v_mfma_f32_16x16x32_bf16 v[86:89], v[86:89], v[60:63], 0
	v_lshl_add_u64 v[190:191], v[192:193], 0, s[98:99]
	global_store_dword v[190:191], v75, off
	v_mul_f32_e32 v72, 0x3fb8aa3b, v76
	v_exp_f32_e32 v76, v72
	s_waitcnt lgkmcnt(0)
	v_mfma_f32_16x16x32_bf16 v[72:75], v[80:83], v[64:67], v[86:89]
	s_nop 2
	s_nop 4
	v_fma_f32 v68, v68, v76, v72
	v_mul_f32_e32 v72, 0x3fb8aa3b, v77
	v_exp_f32_e32 v72, v72
	v_lshl_add_u64 v[194:195], v[194:195], 0, s[100:101]
	global_store_dword v[194:195], v68, off
	v_fma_f32 v72, v69, v72, v73
	v_add_u32_e32 v101, s0, v159
	v_add_u32_e32 v73, v101, v90
	ds_read_b64 v[80:81], v73
	ds_read_b64 v[82:83], v73 offset:32
	v_lshl_add_u64 v[190:191], v[194:195], 0, s[98:99]
	global_store_dword v[190:191], v72, off
	v_mul_f32_e32 v69, 0x3fb8aa3b, v78
	v_exp_f32_e32 v68, v157
	v_exp_f32_e32 v69, v69
	v_xor_b32_e32 v77, 8, v91
	v_pk_mul_f32 v[8:9], v[8:9], v[68:69] op_sel_hi:[1,0]
	v_pk_mul_f32 v[10:11], v[10:11], v[68:69] op_sel_hi:[1,0]
	v_fma_f32 v69, v70, v69, v74
	v_add_u32_e32 v70, s0, v141
	s_waitcnt lgkmcnt(0)
	v_mfma_f32_16x16x32_bf16 v[8:11], v[80:83], v[60:63], v[8:11]
	ds_read_b64 v[80:81], v73 offset:64
	ds_read_b64 v[82:83], v73 offset:96
	v_add_u32_e32 v73, s0, v140
	v_xad_u32 v76, v90, 16, v73
	v_lshl_add_u32 v77, v77, 1, v73
	ds_read_b64 v[86:87], v76
	ds_read_b64 v[88:89], v77
	v_xor_b32_e32 v76, 8, v93
	v_lshl_add_u32 v76, v76, 1, v73
	v_xor_b32_e32 v77, 8, v94
	v_lshl_add_u32 v73, v77, 1, v73
	ds_read_b64 v[96:97], v76
	ds_read_b64 v[98:99], v73
	v_xad_u32 v74, v90, 32, v70
	v_xor_b32_e32 v76, 16, v91
	s_waitcnt lgkmcnt(4)
	v_mfma_f32_16x16x32_bf16 v[8:11], v[80:83], v[64:67], v[8:11]
	v_lshl_add_u32 v76, v76, 1, v70
	ds_read_b64 v[80:81], v74
	ds_read_b64 v[82:83], v76
	v_xor_b32_e32 v74, 16, v93
	v_xor_b32_e32 v76, 16, v94
	v_pk_mul_f32 v[4:5], v[4:5], v[68:69] op_sel_hi:[1,0]
	v_pk_mul_f32 v[6:7], v[6:7], v[68:69] op_sel_hi:[1,0]
	v_lshl_add_u32 v74, v74, 1, v70
	v_lshl_add_u32 v70, v76, 1, v70
	s_waitcnt lgkmcnt(4)
	v_mfma_f32_16x16x32_bf16 v[4:7], v[86:89], v[60:63], v[4:7]
	ds_read_b64 v[86:87], v74
	ds_read_b64 v[88:89], v70
	v_add_u32_e32 v70, s0, v100
	v_pk_mul_f32 v[16:17], v[16:17], v[68:69] op_sel_hi:[1,0]
	v_pk_mul_f32 v[18:19], v[18:19], v[68:69] op_sel_hi:[1,0]
	v_xad_u32 v74, v90, 48, v70
	v_xor_b32_e32 v76, 24, v91
	s_waitcnt lgkmcnt(2)
	v_mfma_f32_16x16x32_bf16 v[16:19], v[80:83], v[60:63], v[16:19]
	v_lshl_add_u32 v76, v76, 1, v70
	ds_read_b64 v[80:81], v74
	ds_read_b64 v[82:83], v76
	v_xor_b32_e32 v74, 24, v93
	v_lshl_add_u32 v74, v74, 1, v70
	v_xor_b32_e32 v76, 24, v94
	v_lshl_add_u64 v[192:193], v[190:191], 0, s[98:99]
	v_mfma_f32_16x16x32_bf16 v[4:7], v[96:99], v[64:67], v[4:7]
	v_lshl_add_u32 v70, v76, 1, v70
	ds_read_b64 v[96:97], v74
	ds_read_b64 v[98:99], v70
	global_store_dword v[192:193], v69, off
	v_xad_u32 v72, v90, 64, v101
	v_xor_b32_e32 v73, 32, v91
	v_mul_f32_e32 v70, 0x3fb8aa3b, v79
	v_lshl_add_u32 v73, v73, 1, v101
	ds_read_b64 v[76:77], v72 offset:9216
	ds_read_b64 v[78:79], v73 offset:9216
	v_pk_mul_f32 v[12:13], v[12:13], v[68:69] op_sel_hi:[1,0]
	v_pk_mul_f32 v[14:15], v[14:15], v[68:69] op_sel_hi:[1,0]
	v_xor_b32_e32 v72, 32, v93
	v_xor_b32_e32 v73, 32, v94
	v_exp_f32_e32 v70, v70
	s_waitcnt lgkmcnt(4)
	v_mfma_f32_16x16x32_bf16 v[12:15], v[80:83], v[60:63], v[12:15]
	v_lshl_add_u32 v72, v72, 1, v101
	v_lshl_add_u32 v73, v73, 1, v101
	s_movk_i32 s0, 0x50
	v_pk_mul_f32 v[24:25], v[24:25], v[68:69] op_sel_hi:[1,0]
	v_pk_mul_f32 v[26:27], v[26:27], v[68:69] op_sel_hi:[1,0]
	ds_read_b64 v[80:81], v72 offset:9216
	ds_read_b64 v[82:83], v73 offset:9216
	v_xad_u32 v72, v90, s0, v101
	v_xor_b32_e32 v73, 40, v91
	s_waitcnt lgkmcnt(2)
	v_mfma_f32_16x16x32_bf16 v[24:27], v[76:79], v[60:63], v[24:27]
	v_lshl_add_u32 v73, v73, 1, v101
	ds_read_b64 v[76:77], v72 offset:11520
	ds_read_b64 v[78:79], v73 offset:11520
	v_xor_b32_e32 v72, 40, v93
	v_lshl_add_u32 v72, v72, 1, v101
	v_xor_b32_e32 v73, 40, v94
	v_fmac_f32_e32 v75, v71, v70
	s_movk_i32 s0, 0x60
	v_xor_b32_e32 v70, 48, v91
	v_mfma_f32_16x16x32_bf16 v[16:19], v[86:89], v[64:67], v[16:19]
	v_lshl_add_u32 v73, v73, 1, v101
	ds_read_b64 v[86:87], v72 offset:11520
	ds_read_b64 v[88:89], v73 offset:11520
	v_pk_mul_f32 v[20:21], v[20:21], v[68:69] op_sel_hi:[1,0]
	v_mfma_f32_16x16x32_bf16 v[12:15], v[96:99], v[64:67], v[12:15]
	v_mul_f32_e64 v22, v22, v68
	v_mul_f32_e64 v23, v23, v68
	v_xad_u32 v69, v90, s0, v101
	v_lshl_add_u32 v72, v70, 1, v101
	ds_read_b64 v[70:71], v69 offset:13824
	ds_read_b64 v[72:73], v72 offset:13824
	v_pk_mul_f32 v[32:33], v[32:33], v[68:69] op_sel_hi:[1,0]
	v_pk_mul_f32 v[34:35], v[34:35], v[68:69] op_sel_hi:[1,0]
	v_xor_b32_e32 v69, 48, v93
	v_lshl_add_u32 v69, v69, 1, v101
	v_xor_b32_e32 v74, 48, v94
	s_waitcnt lgkmcnt(0)
	v_mfma_f32_16x16x32_bf16 v[32:35], v[70:73], v[60:63], v[32:35]
	s_movk_i32 s0, 0x70
	v_xor_b32_e32 v70, 56, v91
	v_lshl_add_u32 v74, v74, 1, v101
	v_mfma_f32_16x16x32_bf16 v[20:23], v[76:79], v[60:63], v[20:23]
	ds_read_b64 v[76:77], v69 offset:13824
	ds_read_b64 v[78:79], v74 offset:13824
	v_xad_u32 v69, v90, s0, v101
	v_lshl_add_u32 v72, v70, 1, v101
	ds_read_b64 v[70:71], v69 offset:16128
	ds_read_b64 v[72:73], v72 offset:16128
	v_xor_b32_e32 v69, 56, v93
	v_lshl_add_u32 v69, v69, 1, v101
	v_xor_b32_e32 v74, 56, v94
	v_mfma_f32_16x16x32_bf16 v[24:27], v[80:83], v[64:67], v[24:27]
	v_lshl_add_u32 v74, v74, 1, v101
	ds_read_b64 v[80:81], v69 offset:16128
	ds_read_b64 v[82:83], v74 offset:16128
	v_pk_mul_f32 v[28:29], v[28:29], v[68:69] op_sel_hi:[1,0]
	v_pk_mul_f32 v[30:31], v[30:31], v[68:69] op_sel_hi:[1,0]
	v_mfma_f32_16x16x32_bf16 v[20:23], v[86:89], v[64:67], v[20:23]
	v_lshl_add_u64 v[190:191], v[192:193], 0, s[98:99]
	s_waitcnt lgkmcnt(2)
	v_mfma_f32_16x16x32_bf16 v[28:31], v[70:73], v[60:63], v[28:31]
	global_store_dword v[190:191], v75, off
	v_mfma_f32_16x16x32_bf16 v[32:35], v[76:79], v[64:67], v[32:35]
	s_waitcnt lgkmcnt(0)
	v_mfma_f32_16x16x32_bf16 v[28:31], v[80:83], v[64:67], v[28:31]
	s_and_saveexec_b64 s[0:1], vcc
	s_cbranch_execz .LBB0_644
	v_and_b32_e32 v0, 7, v3
	v_ashrrev_i32_e32 v1, 3, v3
	v_cmp_eq_u32_e32 vcc, 0, v0
	s_and_saveexec_b64 s[12:13], vcc
	s_cbranch_execz .LBB0_643
	s_and_b64 s[66:67], s[14:15], exec
	s_cselect_b32 s66, s55, s64
	s_add_i32 s67, 16, 0x1c900
	s_add_i32 vcc_lo, 16, 0x25900
	s_and_b64 s[64:65], s[14:15], exec
	s_cselect_b32 s64, vcc_lo, s67
	v_lshlrev_b32_e32 v3, 2, v1
	v_add_u32_e32 v60, s64, v3
	v_add_u32_e32 v3, s66, v3
	s_waitcnt vmcnt(17)
	ds_write_b32 v3, v122
	ds_write_b32 v60, v110
	s_branch .LBB0_643
